# clean_k6 + next layer's w_down weights converted by the 7 non-polling waves in the barrier shadow of 3 seams per layer (prologue skips them)
# baseline (speedup 1.0000x reference)
; __device__ __forceinline__ void transpose_item64(const float* Wf, int Nsrc, int ca, int nva, int cb, int nvb, int K, bf16* WTf, int drow0, int k0, LAS unsigned char* scr, int lane, const float* gainf = nullptr) {
;     const GAS float* W = (const GAS float*)Wf; GAS bf16* WT = (GAS bf16*)WTf;
;     const int sub = (lane >> 3) & 1, c4 = 4 * (lane & 7), g = lane >> 4, nl = 32 * sub + c4;
;     const bool ok = c4 < (sub ? nvb : nva);
;     const GAS float* src = W + (size_t)(k0 + 2 * g) * Nsrc + (sub ? cb : ca) + c4;
;     f32x4 v[16];
; #pragma unroll
;     for (int i = 0; i < 16; ++i) v[i] = ok ? *(const GAS f32x4*)(src + (size_t)(8 * (i >> 1) + (i & 1)) * Nsrc) : (f32x4){0.f, 0.f, 0.f, 0.f};
;     if (gainf) { const GAS float* gp = (const GAS float*)gainf + k0 + 2 * g;
; #pragma unroll
;         for (int i = 0; i < 16; ++i) v[i] = v[i] * gp[8 * (i >> 1) + (i & 1)]; }
; #pragma unroll
; __device__ __forceinline__ void convert_item(Frame& F, unsigned char* w, int l, int r, LAS unsigned char* scr) {
;     unsigned char* wl = w + WS_W + (size_t)l * LW_STRIDE;
;     if (r < IT_GU) { conv_gu(inptr(F, 3) + (size_t)l * D * FF, inptr(F, 4) + (size_t)l * D * FF, (bf16*)(wl + LW_GU1), r, scr, F.lane, inptr(F, 2) + (size_t)l * D); return; } r -= IT_GU;
;     if (r < IT_D) { conv_plain(inptr(F, 5) + (size_t)l * FF * D, FF, D, (bf16*)(wl + LW_D1), r, scr, F.lane); return; } r -= IT_D;
;     if (r < IT_IN) { conv_in(inptr(F, 7) + (size_t)l * D * IN_W, (bf16*)(wl + LW_IN), r, scr, F.lane, inptr(F, 6) + (size_t)l * D); return; } r -= IT_IN;
;     if (r < IT_OUT) { conv_plain(inptr(F, 16) + (size_t)l * D * D, D, D, (bf16*)(wl + LW_OUT), r, scr, F.lane, inptr(F, 14) + (size_t)l * 1024, inptr(F, 15) + (size_t)l * 1024); return; } r -= IT_OUT;
;     if (r < IT_GU) { conv_gu(inptr(F, 18) + (size_t)l * D * FF, inptr(F, 19) + (size_t)l * D * FF, (bf16*)(wl + LW_GU2), r, scr, F.lane, inptr(F, 17) + (size_t)l * D); return; } r -= IT_GU;
;     conv_plain(inptr(F, 20) + (size_t)l * FF * D, FF, D, (bf16*)(wl + LW_D2), r, scr, F.lane);
; }
; __device__ __forceinline__ void convert_layer(Frame& F, unsigned char* w, int l) {
;     LAS unsigned char* scr = F.lds + RING_OFF + F.wave * 16384;
;     const int gw = F.vcu * NWAVES + F.wave, NGW = F.G * NWAVES;
;     if (F.G == 256) { for (int q = gw; q < IT_LAYER - R_IDLE; q += NGW) convert_item(F, w, l, q < GU2_BASE ? q : q + R_IDLE, scr); }
.LBB0_200:
	s_add_i32 s0, s37, 0x1800
	s_cmpk_lt_i32 s37, 0x2e00
	s_cselect_b32 s51, s37, s0
	s_cmp_eq_u32 s36, 0
	s_cbranch_scc1 .Lpk_keep
	s_cmpk_lt_u32 s51, 0x1600
	s_cbranch_scc1 .Lpk_keep
	s_cmpk_lt_u32 s51, 0x2100
	s_cbranch_scc1 .LBB0_199
	s_cmpk_lt_u32 s51, 0x4600
	s_cbranch_scc1 .Lpk_keep
	s_branch .LBB0_199
.Lpk_keep:
	s_cmpk_gt_i32 s51, 0x15ff
	s_mov_b64 s[8:9], -1
	s_cbranch_scc0 .LBB0_215
	s_cmpk_gt_u32 s51, 0x20ff
	s_cbranch_scc0 .LBB0_271
	s_cmpk_gt_u32 s51, 0x29ff
	s_cbranch_scc0 .LBB0_220
	s_cmpk_gt_u32 s51, 0x2dff
	s_cbranch_scc0 .LBB0_212
	s_cmpk_gt_u32 s51, 0x43ff
	s_cbranch_scc0 .LBB0_206
	v_mov_b32_e32 v1, s54
	ds_read_b32 v1, v1
	v_mov_b32_e32 v2, s55
	ds_read_b32 v2, v2
	v_mov_b32_e32 v3, v0
	v_mov_b32_e32 v5, v0
	s_waitcnt lgkmcnt(1)
	v_readfirstlane_b32 s0, v1
	s_add_u32 s0, s0, s35
	s_waitcnt lgkmcnt(0)
	v_readfirstlane_b32 s1, v2
	s_addc_u32 s1, s1, s34
	s_lshl_b32 s9, s51, 1
	s_add_i32 s9, s9, 0x7fff7800
	s_lshl_b32 s8, s51, 6
	s_and_b32 s9, s9, 0x7fffffc0
	s_and_b32 s8, s8, 0x7c0
	v_or_b32_e32 v2, s9, v138
	v_lshlrev_b64 v[2:3], 13, v[2:3]
	v_or_b32_e32 v1, s8, v135
	v_lshl_add_u64 v[2:3], s[0:1], 0, v[2:3]
	v_lshlrev_b32_e32 v4, 2, v1
	v_lshl_add_u64 v[2:3], v[2:3], 0, v[4:5]
	v_mov_b32_e32 v143, v0
	s_waitcnt vmcnt(11)
	v_lshl_add_u64 v[58:59], v[2:3], 0, v[142:143]
	v_add_co_u32_e32 v6, vcc, s56, v58
	global_load_dwordx4 v[2:5], v[58:59], off
	s_nop 0
	v_addc_co_u32_e32 v7, vcc, 0, v59, vcc
	global_load_dwordx4 v[6:9], v[6:7], off
	v_add_co_u32_e32 v10, vcc, s57, v58
	s_lshl_b32 s20, s9, 1
	s_nop 0
	v_addc_co_u32_e32 v11, vcc, 0, v59, vcc
	v_add_co_u32_e32 v14, vcc, s58, v58
	s_waitcnt vmcnt(1)
	v_bfe_u32 v1, v2, 16, 1
	v_addc_co_u32_e32 v15, vcc, 0, v59, vcc
	global_load_dwordx4 v[10:13], v[10:11], off
	s_nop 0
	global_load_dwordx4 v[14:17], v[14:15], off
	v_add_co_u32_e32 v18, vcc, s59, v58
	v_add3_u32 v1, v2, v1, s71
	s_nop 0
	v_addc_co_u32_e32 v19, vcc, 0, v59, vcc
	v_add_co_u32_e32 v22, vcc, s60, v58
	s_waitcnt vmcnt(2)
	v_bfe_u32 v2, v6, 16, 1
	v_addc_co_u32_e32 v23, vcc, 0, v59, vcc
	global_load_dwordx4 v[18:21], v[18:19], off
	s_nop 0
	global_load_dwordx4 v[22:25], v[22:23], off
	v_add_co_u32_e32 v26, vcc, s61, v58
	v_lshrrev_b32_e32 v1, 16, v1
	s_nop 0
	v_addc_co_u32_e32 v27, vcc, 0, v59, vcc
	v_add_co_u32_e32 v30, vcc, s62, v58
	v_add3_u32 v2, v6, v2, s71
	s_nop 0
	v_addc_co_u32_e32 v31, vcc, 0, v59, vcc
	global_load_dwordx4 v[26:29], v[26:27], off
	s_nop 0
	global_load_dwordx4 v[30:33], v[30:31], off
	v_add_co_u32_e32 v34, vcc, s63, v58
	v_and_or_b32 v1, v2, s72, v1
	s_nop 0
	v_addc_co_u32_e32 v35, vcc, 0, v59, vcc
	v_add_co_u32_e32 v38, vcc, s64, v58
	v_bfe_u32 v2, v3, 16, 1
	s_nop 0
	v_addc_co_u32_e32 v39, vcc, 0, v59, vcc
	global_load_dwordx4 v[34:37], v[34:35], off
	s_nop 0
	global_load_dwordx4 v[38:41], v[38:39], off
	v_add_co_u32_e32 v42, vcc, s65, v58
	v_add3_u32 v2, v3, v2, s71
	s_nop 0
	v_addc_co_u32_e32 v43, vcc, 0, v59, vcc
	v_add_co_u32_e32 v46, vcc, s66, v58
	v_bfe_u32 v3, v7, 16, 1
	s_nop 0
	v_addc_co_u32_e32 v47, vcc, 0, v59, vcc
	global_load_dwordx4 v[42:45], v[42:43], off
	s_nop 0
	global_load_dwordx4 v[46:49], v[46:47], off
	v_add_co_u32_e32 v50, vcc, s67, v58
	v_lshrrev_b32_e32 v2, 16, v2
	s_nop 0
	v_addc_co_u32_e32 v51, vcc, 0, v59, vcc
	v_add_co_u32_e32 v54, vcc, s68, v58
	v_add3_u32 v3, v7, v3, s71
	s_nop 0
	v_addc_co_u32_e32 v55, vcc, 0, v59, vcc
	global_load_dwordx4 v[50:53], v[50:51], off
	s_nop 0
	global_load_dwordx4 v[54:57], v[54:55], off
	v_and_or_b32 v2, v3, s72, v2
	v_bfe_u32 v3, v4, 16, 1
	v_add3_u32 v3, v4, v3, s71
	v_bfe_u32 v4, v8, 16, 1
	v_lshrrev_b32_e32 v3, 16, v3
	v_add3_u32 v4, v8, v4, s71
	v_and_or_b32 v3, v4, s72, v3
	v_bfe_u32 v4, v5, 16, 1
	v_add3_u32 v4, v5, v4, s71
	v_bfe_u32 v5, v9, 16, 1
	v_lshrrev_b32_e32 v4, 16, v4
	v_add3_u32 v5, v9, v5, s71
	v_add_co_u32_e32 v60, vcc, s69, v58
	v_and_or_b32 v4, v5, s72, v4
	s_nop 0
	v_addc_co_u32_e32 v61, vcc, 0, v59, vcc
	v_add_co_u32_e32 v62, vcc, s70, v58
	v_mov_b32_e32 v7, v0
	s_nop 0
	v_addc_co_u32_e32 v63, vcc, 0, v59, vcc
	global_load_dwordx4 v[58:61], v[60:61], off
	s_nop 0
	global_load_dwordx4 v[62:65], v[62:63], off
	s_waitcnt vmcnt(13)
	v_bfe_u32 v5, v10, 16, 1
	v_add3_u32 v5, v10, v5, s71
	s_waitcnt vmcnt(12)
	v_bfe_u32 v6, v14, 16, 1
	v_lshrrev_b32_e32 v5, 16, v5
	v_add3_u32 v6, v14, v6, s71
	v_and_or_b32 v5, v6, s72, v5
	ds_write2_b32 v139, v1, v5 offset1:4
	v_bfe_u32 v1, v11, 16, 1
	v_add3_u32 v1, v11, v1, s71
	v_bfe_u32 v5, v15, 16, 1
	v_lshrrev_b32_e32 v1, 16, v1
	v_add3_u32 v5, v15, v5, s71
	v_and_or_b32 v1, v5, s72, v1
	ds_write2_b32 v139, v2, v1 offset0:36 offset1:40
	v_bfe_u32 v1, v12, 16, 1
	v_add3_u32 v1, v12, v1, s71
	v_bfe_u32 v2, v16, 16, 1
	v_lshrrev_b32_e32 v1, 16, v1
	v_add3_u32 v2, v16, v2, s71
	v_and_or_b32 v1, v2, s72, v1
	ds_write2_b32 v139, v3, v1 offset0:72 offset1:76
	v_bfe_u32 v1, v13, 16, 1
	v_add3_u32 v1, v13, v1, s71
	v_bfe_u32 v2, v17, 16, 1
	v_lshrrev_b32_e32 v1, 16, v1
	v_add3_u32 v2, v17, v2, s71
	v_and_or_b32 v1, v2, s72, v1
	ds_write2_b32 v139, v4, v1 offset0:108 offset1:112
	s_waitcnt vmcnt(11)
	v_bfe_u32 v1, v18, 16, 1
	v_add3_u32 v1, v18, v1, s71
	s_waitcnt vmcnt(10)
	v_bfe_u32 v2, v22, 16, 1
	v_lshrrev_b32_e32 v1, 16, v1
	v_add3_u32 v2, v22, v2, s71
	v_and_or_b32 v1, v2, s72, v1
	v_bfe_u32 v2, v19, 16, 1
	v_add3_u32 v2, v19, v2, s71
	v_bfe_u32 v3, v23, 16, 1
	v_lshrrev_b32_e32 v2, 16, v2
	v_add3_u32 v3, v23, v3, s71
	v_and_or_b32 v2, v3, s72, v2
	v_bfe_u32 v3, v20, 16, 1
	v_add3_u32 v3, v20, v3, s71
	v_bfe_u32 v4, v24, 16, 1
	v_lshrrev_b32_e32 v3, 16, v3
	v_add3_u32 v4, v24, v4, s71
	v_and_or_b32 v3, v4, s72, v3
	v_bfe_u32 v4, v21, 16, 1
	v_add3_u32 v4, v21, v4, s71
	v_bfe_u32 v5, v25, 16, 1
	v_lshrrev_b32_e32 v4, 16, v4
	v_add3_u32 v5, v25, v5, s71
	v_and_or_b32 v4, v5, s72, v4
	s_waitcnt vmcnt(9)
; #define GAS __attribute__((address_space(1)))
; #define LAS __attribute__((address_space(3)))
; #define LDS_WAIT() asm volatile("s_waitcnt lgkmcnt(0)" ::: "memory")
; __device__ __forceinline__ unsigned pk2(float lo, float hi) { return f2bf(lo) | (f2bf(hi) << 16); }
; __device__ __forceinline__ void transpose_item64(const float* Wf, int Nsrc, int ca, int nva, int cb, int nvb, int K, bf16* WTf, int drow0, int k0, LAS unsigned char* scr, int lane, const float* gainf = nullptr) {
;     ...
; #pragma unroll
;     for (int m = 0; m < 8; ++m)
; #pragma unroll
;         for (int j = 0; j < 4; ++j) *(LAS unsigned*)(scr + (nl + j) * TP_PITCH + (8 * m + 2 * g) * 2) = pk2(v[2 * m][j], v[2 * m + 1][j]);
;     LDS_WAIT(); asm volatile("" ::: "memory");
; #pragma unroll
;     for (int t = 0; t < 8; ++t) { const int id = lane + 64 * t, n = id >> 3, c = id & 7;
;         const v4u o = *(const LAS v4u*)(scr + n * TP_PITCH + 16 * c);
;         *(GAS v4u*)(WT + (size_t)(drow0 + n) * K + k0 + 8 * c) = o; }
;     LDS_WAIT(); asm volatile("" ::: "memory");
	v_bfe_u32 v5, v26, 16, 1
	v_add3_u32 v5, v26, v5, s71
	s_waitcnt vmcnt(8)
	v_bfe_u32 v6, v30, 16, 1
	v_lshrrev_b32_e32 v5, 16, v5
	v_add3_u32 v6, v30, v6, s71
	v_and_or_b32 v5, v6, s72, v5
	ds_write2_b32 v139, v1, v5 offset0:8 offset1:12
	v_bfe_u32 v1, v27, 16, 1
	v_add3_u32 v1, v27, v1, s71
	v_bfe_u32 v5, v31, 16, 1
	v_lshrrev_b32_e32 v1, 16, v1
	v_add3_u32 v5, v31, v5, s71
	v_and_or_b32 v1, v5, s72, v1
	ds_write2_b32 v139, v2, v1 offset0:44 offset1:48
	v_bfe_u32 v1, v28, 16, 1
	v_add3_u32 v1, v28, v1, s71
	v_bfe_u32 v2, v32, 16, 1
	v_lshrrev_b32_e32 v1, 16, v1
	v_add3_u32 v2, v32, v2, s71
	v_and_or_b32 v1, v2, s72, v1
	ds_write2_b32 v139, v3, v1 offset0:80 offset1:84
	v_bfe_u32 v1, v29, 16, 1
	v_add3_u32 v1, v29, v1, s71
	v_bfe_u32 v2, v33, 16, 1
	v_lshrrev_b32_e32 v1, 16, v1
	v_add3_u32 v2, v33, v2, s71
	v_and_or_b32 v1, v2, s72, v1
	ds_write2_b32 v139, v4, v1 offset0:116 offset1:120
	s_waitcnt vmcnt(7)
	v_bfe_u32 v1, v34, 16, 1
	v_add3_u32 v1, v34, v1, s71
	s_waitcnt vmcnt(6)
	v_bfe_u32 v2, v38, 16, 1
	v_lshrrev_b32_e32 v1, 16, v1
	v_add3_u32 v2, v38, v2, s71
	v_and_or_b32 v1, v2, s72, v1
	v_bfe_u32 v2, v35, 16, 1
	v_add3_u32 v2, v35, v2, s71
	v_bfe_u32 v3, v39, 16, 1
	v_lshrrev_b32_e32 v2, 16, v2
	v_add3_u32 v3, v39, v3, s71
	v_and_or_b32 v2, v3, s72, v2
	v_bfe_u32 v3, v36, 16, 1
	v_add3_u32 v3, v36, v3, s71
	v_bfe_u32 v4, v40, 16, 1
	v_lshrrev_b32_e32 v3, 16, v3
	v_add3_u32 v4, v40, v4, s71
	v_and_or_b32 v3, v4, s72, v3
	v_bfe_u32 v4, v37, 16, 1
	v_add3_u32 v4, v37, v4, s71
	v_bfe_u32 v5, v41, 16, 1
	v_lshrrev_b32_e32 v4, 16, v4
	v_add3_u32 v5, v41, v5, s71
	v_and_or_b32 v4, v5, s72, v4
	s_waitcnt vmcnt(5)
	v_bfe_u32 v5, v42, 16, 1
	v_add3_u32 v5, v42, v5, s71
	s_waitcnt vmcnt(4)
	v_bfe_u32 v6, v46, 16, 1
	v_lshrrev_b32_e32 v5, 16, v5
	v_add3_u32 v6, v46, v6, s71
	v_and_or_b32 v5, v6, s72, v5
	ds_write2_b32 v139, v1, v5 offset0:16 offset1:20
	v_bfe_u32 v1, v43, 16, 1
	v_add3_u32 v1, v43, v1, s71
	v_bfe_u32 v5, v47, 16, 1
	v_lshrrev_b32_e32 v1, 16, v1
	v_add3_u32 v5, v47, v5, s71
	v_and_or_b32 v1, v5, s72, v1
	ds_write2_b32 v139, v2, v1 offset0:52 offset1:56
	v_bfe_u32 v1, v44, 16, 1
	v_add3_u32 v1, v44, v1, s71
	v_bfe_u32 v2, v48, 16, 1
	v_lshrrev_b32_e32 v1, 16, v1
	v_add3_u32 v2, v48, v2, s71
	v_and_or_b32 v1, v2, s72, v1
	ds_write2_b32 v139, v3, v1 offset0:88 offset1:92
	v_bfe_u32 v1, v45, 16, 1
	v_add3_u32 v1, v45, v1, s71
	v_bfe_u32 v2, v49, 16, 1
	v_lshrrev_b32_e32 v1, 16, v1
	v_add3_u32 v2, v49, v2, s71
	v_and_or_b32 v1, v2, s72, v1
	ds_write2_b32 v139, v4, v1 offset0:124 offset1:128
	s_waitcnt vmcnt(3)
	v_bfe_u32 v1, v50, 16, 1
	v_add3_u32 v1, v50, v1, s71
	s_waitcnt vmcnt(2)
	v_bfe_u32 v2, v54, 16, 1
	v_lshrrev_b32_e32 v1, 16, v1
	v_add3_u32 v2, v54, v2, s71
	v_and_or_b32 v1, v2, s72, v1
	v_bfe_u32 v2, v51, 16, 1
	v_add3_u32 v2, v51, v2, s71
	v_bfe_u32 v3, v55, 16, 1
	v_lshrrev_b32_e32 v2, 16, v2
	v_add3_u32 v3, v55, v3, s71
	v_and_or_b32 v2, v3, s72, v2
	v_bfe_u32 v3, v52, 16, 1
	v_add3_u32 v3, v52, v3, s71
	v_bfe_u32 v4, v56, 16, 1
	v_lshrrev_b32_e32 v3, 16, v3
	v_add3_u32 v4, v56, v4, s71
	v_and_or_b32 v3, v4, s72, v3
	v_bfe_u32 v4, v53, 16, 1
	v_add3_u32 v4, v53, v4, s71
	v_bfe_u32 v5, v57, 16, 1
	v_lshrrev_b32_e32 v4, 16, v4
	v_add3_u32 v5, v57, v5, s71
	v_and_or_b32 v4, v5, s72, v4
	s_waitcnt vmcnt(1)
	v_bfe_u32 v5, v58, 16, 1
	v_add3_u32 v5, v58, v5, s71
	s_waitcnt vmcnt(0)
	v_bfe_u32 v6, v62, 16, 1
	v_lshrrev_b32_e32 v5, 16, v5
	v_add3_u32 v6, v62, v6, s71
	v_and_or_b32 v5, v6, s72, v5
	ds_write2_b32 v139, v1, v5 offset0:24 offset1:28
	v_bfe_u32 v1, v59, 16, 1
	v_add3_u32 v1, v59, v1, s71
	v_bfe_u32 v5, v63, 16, 1
	v_lshrrev_b32_e32 v1, 16, v1
	v_add3_u32 v5, v63, v5, s71
	v_and_or_b32 v1, v5, s72, v1
	ds_write2_b32 v139, v2, v1 offset0:60 offset1:64
	v_bfe_u32 v1, v60, 16, 1
	v_add3_u32 v1, v60, v1, s71
	v_bfe_u32 v2, v64, 16, 1
	v_lshrrev_b32_e32 v1, 16, v1
	v_add3_u32 v2, v64, v2, s71
	v_and_or_b32 v1, v2, s72, v1
	ds_write2_b32 v139, v3, v1 offset0:96 offset1:100
	v_bfe_u32 v1, v61, 16, 1
	v_add3_u32 v1, v61, v1, s71
	v_bfe_u32 v2, v65, 16, 1
	v_lshrrev_b32_e32 v1, 16, v1
	v_add3_u32 v2, v65, v2, s71
	v_and_or_b32 v1, v2, s72, v1
	ds_write2_b32 v139, v4, v1 offset0:132 offset1:136
	s_waitcnt lgkmcnt(0)
	ds_read_b128 v[2:5], v164
	v_or_b32_e32 v1, s8, v133
	v_lshl_add_u64 v[10:11], v[146:147], 0, s[20:21]
	v_mul_u32_u24_e32 v6, 0x2c00, v1
	v_lshl_add_u64 v[12:13], v[10:11], 0, v[6:7]
	ds_read_b128 v[6:9], v164 offset:1152
	v_or_b32_e32 v1, s8, v156
	s_waitcnt lgkmcnt(1)
	global_store_dwordx4 v[12:13], v[2:5], off
	s_nop 1
	v_mul_u32_u24_e32 v2, 0x2c00, v1
	v_mov_b32_e32 v3, v0
	v_lshl_add_u64 v[2:3], v[10:11], 0, v[2:3]
	s_waitcnt lgkmcnt(0)
	global_store_dwordx4 v[2:3], v[6:9], off
	ds_read_b128 v[2:5], v164 offset:2304
	v_or_b32_e32 v1, s8, v157
	v_mul_u32_u24_e32 v6, 0x2c00, v1
	v_mov_b32_e32 v7, v0
	v_lshl_add_u64 v[12:13], v[10:11], 0, v[6:7]
	ds_read_b128 v[6:9], v164 offset:3456
	v_or_b32_e32 v1, s8, v158
	s_waitcnt lgkmcnt(1)
	global_store_dwordx4 v[12:13], v[2:5], off
	s_nop 1
	v_mul_u32_u24_e32 v2, 0x2c00, v1
	v_mov_b32_e32 v3, v0
	v_lshl_add_u64 v[2:3], v[10:11], 0, v[2:3]
	s_waitcnt lgkmcnt(0)
	global_store_dwordx4 v[2:3], v[6:9], off
	ds_read_b128 v[2:5], v164 offset:4608
	v_or_b32_e32 v1, s8, v159
	v_mul_u32_u24_e32 v6, 0x2c00, v1
	v_mov_b32_e32 v7, v0
	v_lshl_add_u64 v[12:13], v[10:11], 0, v[6:7]
	ds_read_b128 v[6:9], v164 offset:5760
	v_or_b32_e32 v1, s8, v160
	s_waitcnt lgkmcnt(1)
	global_store_dwordx4 v[12:13], v[2:5], off
	s_nop 1
	v_mul_u32_u24_e32 v2, 0x2c00, v1
	v_mov_b32_e32 v3, v0
	v_lshl_add_u64 v[2:3], v[10:11], 0, v[2:3]
	s_waitcnt lgkmcnt(0)
	global_store_dwordx4 v[2:3], v[6:9], off
	ds_read_b128 v[2:5], v164 offset:6912
	v_or_b32_e32 v1, s8, v161
	v_mul_u32_u24_e32 v6, 0x2c00, v1
	v_mov_b32_e32 v7, v0
	v_lshl_add_u64 v[12:13], v[10:11], 0, v[6:7]
	ds_read_b128 v[6:9], v164 offset:8064
	v_or_b32_e32 v1, s8, v162
	s_waitcnt lgkmcnt(1)
	global_store_dwordx4 v[12:13], v[2:5], off
	s_mov_b64 s[8:9], 0
	s_nop 0
	v_mul_u32_u24_e32 v2, 0x2c00, v1
	v_mov_b32_e32 v3, v0
	v_lshl_add_u64 v[2:3], v[10:11], 0, v[2:3]
	s_waitcnt lgkmcnt(0)
	global_store_dwordx4 v[2:3], v[6:9], off
	s_waitcnt lgkmcnt(0)

; #define GAS __attribute__((address_space(1)))
; #define LAS __attribute__((address_space(3)))
; #define LDS_WAIT() asm volatile("s_waitcnt lgkmcnt(0)" ::: "memory")
; __device__ __forceinline__ unsigned pk2(float lo, float hi) { return f2bf(lo) | (f2bf(hi) << 16); }
; __device__ __forceinline__ void xcd_barrier(const XcdBarrier& b) {
;     ...
;     }
;     __syncthreads();
; __device__ __forceinline__ void transpose_item64(const float* Wf, int Nsrc, int ca, int nva, int cb, int nvb, int K, bf16* WTf, int drow0, int k0, LAS unsigned char* scr, int lane, const float* gainf = nullptr) {
;     const GAS float* W = (const GAS float*)Wf; GAS bf16* WT = (GAS bf16*)WTf;
;     const int sub = (lane >> 3) & 1, c4 = 4 * (lane & 7), g = lane >> 4, nl = 32 * sub + c4;
;     const bool ok = c4 < (sub ? nvb : nva);
;     const GAS float* src = W + (size_t)(k0 + 2 * g) * Nsrc + (sub ? cb : ca) + c4;
;     f32x4 v[16];
; #pragma unroll
;     for (int i = 0; i < 16; ++i) v[i] = ok ? *(const GAS f32x4*)(src + (size_t)(8 * (i >> 1) + (i & 1)) * Nsrc) : (f32x4){0.f, 0.f, 0.f, 0.f};
;     if (gainf) { const GAS float* gp = (const GAS float*)gainf + k0 + 2 * g;
; #pragma unroll
;         for (int i = 0; i < 16; ++i) v[i] = v[i] * gp[8 * (i >> 1) + (i & 1)]; }
; #pragma unroll
;     for (int m = 0; m < 8; ++m)
; #pragma unroll
;         for (int j = 0; j < 4; ++j) *(LAS unsigned*)(scr + (nl + j) * TP_PITCH + (8 * m + 2 * g) * 2) = pk2(v[2 * m][j], v[2 * m + 1][j]);
;     LDS_WAIT(); asm volatile("" ::: "memory");
; #pragma unroll
;     for (int t = 0; t < 8; ++t) { const int id = lane + 64 * t, n = id >> 3, c = id & 7;
;         const v4u o = *(const LAS v4u*)(scr + n * TP_PITCH + 16 * c);
;         *(GAS v4u*)(WT + (size_t)(drow0 + n) * K + k0 + 8 * c) = o; }
;     LDS_WAIT(); asm volatile("" ::: "memory");
.LBB0_452:
	s_or_b64 exec, exec, s[6:7]
	s_waitcnt vmcnt(0)
	s_branch .LBB0_453
.Lcv_0:
	s_mov_b64 exec, -1
	v_readlane_b32 s2, v255, 2
	s_getreg_b32 s3, hwreg(HW_REG_HW_ID, 0, 6)
	s_nop 3
	s_cmp_ge_u32 s2, 3
	s_cbranch_scc1 .Lcv_done_0
	s_add_i32 s2, s2, 1
	s_lshl_b32 s3, s3, 2
	s_add_i32 s3, s3, 0x20500
	v_mov_b32_e32 v20, s3
	v_mov_b32_e32 v21, 0x20428
	v_mov_b32_e32 v28, 0x204a0
	v_mov_b32_e32 v29, 0x204b0
	ds_read_b32 v20, v20
	ds_read_b64 v[22:23], v21
	ds_read_b64 v[24:25], v28
	ds_read_b64 v[26:27], v29
	v_readlane_b32 s10, v254, 0
	s_waitcnt lgkmcnt(0)
	v_readfirstlane_b32 s3, v20
	v_readfirstlane_b32 s4, v22
	v_readfirstlane_b32 s5, v23
	v_readfirstlane_b32 s6, v24
	v_readfirstlane_b32 s7, v25
	v_readfirstlane_b32 s8, v26
	v_readfirstlane_b32 s9, v27
	s_nop 3
	s_mul_i32 s10, s10, 7
	s_add_i32 s10, s10, s3
	s_add_i32 s10, s10, -1
	s_lshl_b32 s18, s3, 14
	s_mov_b32 s11, 0x2d00000
	s_cmpk_lt_u32 s10, 0xb00
	s_cbranch_scc1 .Lcv_go_0
	s_cmpk_ge_u32 s10, 0x1400
	s_cbranch_scc1 .Lcv_done_0
	s_add_i32 s10, s10, 0xfffff700
	s_mov_b64 s[4:5], s[6:7]
	s_mov_b32 s11, 0x8900000
.Lcv_go_0:
	s_mul_i32 s13, s2, 0x2c00000
	s_add_u32 s4, s4, s13
	s_addc_u32 s5, s5, 0
	s_mul_i32 s13, s2, 0x9e00000
	s_add_u32 s8, s8, s13
	s_addc_u32 s9, s9, 0
	s_add_u32 s8, s8, s11
	s_addc_u32 s9, s9, 0
	s_lshr_b32 s14, s10, 5
	s_and_b32 s15, s10, 31
	s_mul_i32 s13, s15, 0xb0000
	s_lshl_b32 s16, s14, 7
	s_add_u32 s8, s8, s13
	s_addc_u32 s9, s9, 0
	s_add_u32 s8, s8, s16
	s_addc_u32 s9, s9, 0
	s_lshl_b32 s16, s14, 6
	s_lshl_b32 s17, s15, 6
	v_mbcnt_lo_u32_b32 v20, -1, 0
	v_mbcnt_hi_u32_b32 v20, -1, v20
	v_lshrrev_b32_e32 v21, 4, v20
	v_bfe_u32 v22, v20, 3, 1
	v_and_b32_e32 v23, 7, v20
	v_lshlrev_b32_e32 v24, 2, v23
	v_lshl_add_u32 v24, v22, 5, v24
	v_lshl_add_u32 v25, v21, 1, s16
	v_lshlrev_b32_e32 v25, 11, v25
	v_add3_u32 v25, v25, v24, s17
	v_lshlrev_b32_e32 v25, 2, v25
	v_add_u32_e32 v26, 0x2000, v25
	s_nop 1
	global_load_dwordx4 v[28:31], v25, s[4:5]
	global_load_dwordx4 v[32:35], v26, s[4:5]
	s_add_u32 s4, s4, 0x10000
	s_addc_u32 s5, s5, 0
	s_nop 0
	global_load_dwordx4 v[36:39], v25, s[4:5]
	global_load_dwordx4 v[40:43], v26, s[4:5]
	s_add_u32 s4, s4, 0x10000
	s_addc_u32 s5, s5, 0
	s_nop 0
	global_load_dwordx4 v[44:47], v25, s[4:5]
	global_load_dwordx4 v[48:51], v26, s[4:5]
	s_add_u32 s4, s4, 0x10000
	s_addc_u32 s5, s5, 0
	s_nop 0
	global_load_dwordx4 v[52:55], v25, s[4:5]
	global_load_dwordx4 v[56:59], v26, s[4:5]
	s_add_u32 s4, s4, 0x10000
	s_addc_u32 s5, s5, 0
	s_nop 0
	global_load_dwordx4 v[60:63], v25, s[4:5]
	global_load_dwordx4 v[64:67], v26, s[4:5]
	s_add_u32 s4, s4, 0x10000
	s_addc_u32 s5, s5, 0
	s_nop 0
	global_load_dwordx4 v[68:71], v25, s[4:5]
	global_load_dwordx4 v[72:75], v26, s[4:5]
	s_add_u32 s4, s4, 0x10000
	s_addc_u32 s5, s5, 0
	s_nop 0
	global_load_dwordx4 v[76:79], v25, s[4:5]
	global_load_dwordx4 v[80:83], v26, s[4:5]
	s_add_u32 s4, s4, 0x10000
	s_addc_u32 s5, s5, 0
	s_nop 0
	global_load_dwordx4 v[84:87], v25, s[4:5]
	global_load_dwordx4 v[88:91], v26, s[4:5]
	v_mul_u32_u24_e32 v27, 0x90, v24
	v_lshl_add_u32 v27, v21, 2, v27
	v_add_u32_e32 v27, s18, v27
	v_lshrrev_b32_e32 v96, 3, v20
	v_mul_u32_u24_e32 v97, 0x2c00, v96
	v_lshl_add_u32 v97, v23, 4, v97
	v_mul_u32_u24_e32 v96, 0x90, v96
	v_lshl_add_u32 v96, v23, 4, v96
	v_add_u32_e32 v96, s18, v96
	s_waitcnt vmcnt(14)
	v_cvt_pk_bf16_f32 v100, v28, v32
	ds_write_b32 v27, v100 offset:0
	v_cvt_pk_bf16_f32 v101, v29, v33
	ds_write_b32 v27, v101 offset:144
	v_cvt_pk_bf16_f32 v102, v30, v34
	ds_write_b32 v27, v102 offset:288
	v_cvt_pk_bf16_f32 v103, v31, v35
	ds_write_b32 v27, v103 offset:432
	s_waitcnt vmcnt(12)
	v_cvt_pk_bf16_f32 v104, v36, v40
	ds_write_b32 v27, v104 offset:16
	v_cvt_pk_bf16_f32 v105, v37, v41
	ds_write_b32 v27, v105 offset:160
	v_cvt_pk_bf16_f32 v106, v38, v42
	ds_write_b32 v27, v106 offset:304
	v_cvt_pk_bf16_f32 v107, v39, v43
	ds_write_b32 v27, v107 offset:448
	s_waitcnt vmcnt(10)
	v_cvt_pk_bf16_f32 v100, v44, v48
	ds_write_b32 v27, v100 offset:32
	v_cvt_pk_bf16_f32 v101, v45, v49
	ds_write_b32 v27, v101 offset:176
	v_cvt_pk_bf16_f32 v102, v46, v50
	ds_write_b32 v27, v102 offset:320
	v_cvt_pk_bf16_f32 v103, v47, v51
	ds_write_b32 v27, v103 offset:464
	s_waitcnt vmcnt(8)
	v_cvt_pk_bf16_f32 v104, v52, v56
	ds_write_b32 v27, v104 offset:48
	v_cvt_pk_bf16_f32 v105, v53, v57
	ds_write_b32 v27, v105 offset:192
	v_cvt_pk_bf16_f32 v106, v54, v58
	ds_write_b32 v27, v106 offset:336
	v_cvt_pk_bf16_f32 v107, v55, v59
	ds_write_b32 v27, v107 offset:480
	s_waitcnt vmcnt(6)
	v_cvt_pk_bf16_f32 v100, v60, v64
	ds_write_b32 v27, v100 offset:64
	v_cvt_pk_bf16_f32 v101, v61, v65
	ds_write_b32 v27, v101 offset:208
	v_cvt_pk_bf16_f32 v102, v62, v66
	ds_write_b32 v27, v102 offset:352
	v_cvt_pk_bf16_f32 v103, v63, v67
	ds_write_b32 v27, v103 offset:496
	s_waitcnt vmcnt(4)
	v_cvt_pk_bf16_f32 v104, v68, v72
	ds_write_b32 v27, v104 offset:80
	v_cvt_pk_bf16_f32 v105, v69, v73
	ds_write_b32 v27, v105 offset:224
	v_cvt_pk_bf16_f32 v106, v70, v74
	ds_write_b32 v27, v106 offset:368
	v_cvt_pk_bf16_f32 v107, v71, v75
	ds_write_b32 v27, v107 offset:512
	s_waitcnt vmcnt(2)
	v_cvt_pk_bf16_f32 v100, v76, v80
	ds_write_b32 v27, v100 offset:96
	v_cvt_pk_bf16_f32 v101, v77, v81
	ds_write_b32 v27, v101 offset:240
	v_cvt_pk_bf16_f32 v102, v78, v82
	ds_write_b32 v27, v102 offset:384
	v_cvt_pk_bf16_f32 v103, v79, v83
	ds_write_b32 v27, v103 offset:528
	s_waitcnt vmcnt(0)
	v_cvt_pk_bf16_f32 v104, v84, v88
	ds_write_b32 v27, v104 offset:112
	v_cvt_pk_bf16_f32 v105, v85, v89
	ds_write_b32 v27, v105 offset:256
	v_cvt_pk_bf16_f32 v106, v86, v90
	ds_write_b32 v27, v106 offset:400
	v_cvt_pk_bf16_f32 v107, v87, v91
	ds_write_b32 v27, v107 offset:544
	s_waitcnt lgkmcnt(0)
	ds_read_b128 v[28:31], v96 offset:0
	ds_read_b128 v[32:35], v96 offset:1152
	ds_read_b128 v[36:39], v96 offset:2304
	ds_read_b128 v[40:43], v96 offset:3456
	ds_read_b128 v[44:47], v96 offset:4608
	ds_read_b128 v[48:51], v96 offset:5760
	ds_read_b128 v[52:55], v96 offset:6912
	ds_read_b128 v[56:59], v96 offset:8064
	s_waitcnt lgkmcnt(7)
	global_store_dwordx4 v97, v[28:31], s[8:9]
	s_add_u32 s8, s8, 0x16000
	s_addc_u32 s9, s9, 0
	s_waitcnt lgkmcnt(6)
	global_store_dwordx4 v97, v[32:35], s[8:9]
	s_add_u32 s8, s8, 0x16000
	s_addc_u32 s9, s9, 0
	s_waitcnt lgkmcnt(5)
	global_store_dwordx4 v97, v[36:39], s[8:9]
	s_add_u32 s8, s8, 0x16000
	s_addc_u32 s9, s9, 0
	s_waitcnt lgkmcnt(4)
	global_store_dwordx4 v97, v[40:43], s[8:9]
	s_add_u32 s8, s8, 0x16000
	s_addc_u32 s9, s9, 0
	s_waitcnt lgkmcnt(3)
	global_store_dwordx4 v97, v[44:47], s[8:9]
	s_add_u32 s8, s8, 0x16000
	s_addc_u32 s9, s9, 0
	s_waitcnt lgkmcnt(2)
	global_store_dwordx4 v97, v[48:51], s[8:9]
	s_add_u32 s8, s8, 0x16000
	s_addc_u32 s9, s9, 0
	s_waitcnt lgkmcnt(1)
	global_store_dwordx4 v97, v[52:55], s[8:9]
	s_add_u32 s8, s8, 0x16000
	s_addc_u32 s9, s9, 0
	s_waitcnt lgkmcnt(0)
	global_store_dwordx4 v97, v[56:59], s[8:9]
.Lcv_done_0:
.LBB0_453:
	s_or_b64 exec, exec, s[0:1]
	v_readlane_b32 s4, v254, 0
	s_waitcnt lgkmcnt(0)
	s_barrier

; #define LAS __attribute__((address_space(3)))
; __device__ __forceinline__ void conv_plain(const float* W, int K, int N, bf16* WT, int r, LAS unsigned char* scr, int lane, const float* gain_lo = nullptr, const float* gain_hi = nullptr) {
;     const int nrg = N / 64, kb = r / nrg, rg = r % nrg;
;     const float* gain = gain_lo ? (64 * kb < 1024 ? gain_lo : gain_hi - 1024) : nullptr;
;     transpose_item64(W, N, 64 * rg, 32, 64 * rg + 32, 32, K, WT, 64 * rg, 64 * kb, scr, lane, gain);
; __device__ __forceinline__ void convert_item(Frame& F, unsigned char* w, int l, int r, LAS unsigned char* scr) {
;     unsigned char* wl = w + WS_W + (size_t)l * LW_STRIDE;
;     if (r < IT_GU) { conv_gu(inptr(F, 3) + (size_t)l * D * FF, inptr(F, 4) + (size_t)l * D * FF, (bf16*)(wl + LW_GU1), r, scr, F.lane, inptr(F, 2) + (size_t)l * D); return; } r -= IT_GU;
;     if (r < IT_D) { conv_plain(inptr(F, 5) + (size_t)l * FF * D, FF, D, (bf16*)(wl + LW_D1), r, scr, F.lane); return; } r -= IT_D;
;     if (r < IT_IN) { conv_in(inptr(F, 7) + (size_t)l * D * IN_W, (bf16*)(wl + LW_IN), r, scr, F.lane, inptr(F, 6) + (size_t)l * D); return; } r -= IT_IN;
;     if (r < IT_OUT) { conv_plain(inptr(F, 16) + (size_t)l * D * D, D, D, (bf16*)(wl + LW_OUT), r, scr, F.lane, inptr(F, 14) + (size_t)l * 1024, inptr(F, 15) + (size_t)l * 1024); return; } r -= IT_OUT;
;     if (r < IT_GU) { conv_gu(inptr(F, 18) + (size_t)l * D * FF, inptr(F, 19) + (size_t)l * D * FF, (bf16*)(wl + LW_GU2), r, scr, F.lane, inptr(F, 17) + (size_t)l * D); return; } r -= IT_GU;
;     conv_plain(inptr(F, 20) + (size_t)l * FF * D, FF, D, (bf16*)(wl + LW_D2), r, scr, F.lane);
.Lcv_1:
	s_mov_b64 exec, -1
	v_readlane_b32 s2, v255, 2
	s_getreg_b32 s3, hwreg(HW_REG_HW_ID, 0, 6)
	s_nop 3
	s_cmp_ge_u32 s2, 3
	s_cbranch_scc1 .Lcv_done_1
	s_add_i32 s2, s2, 1
	s_lshl_b32 s3, s3, 2
	s_add_i32 s3, s3, 0x20500
	v_mov_b32_e32 v20, s3
	v_mov_b32_e32 v21, 0x20428
	v_mov_b32_e32 v28, 0x204a0
	v_mov_b32_e32 v29, 0x204b0
	ds_read_b32 v20, v20
	ds_read_b64 v[22:23], v21
	ds_read_b64 v[24:25], v28
	ds_read_b64 v[26:27], v29
	v_readlane_b32 s10, v254, 0
	s_waitcnt lgkmcnt(0)
	v_readfirstlane_b32 s3, v20
	v_readfirstlane_b32 s4, v22
	v_readfirstlane_b32 s5, v23
	v_readfirstlane_b32 s6, v24
	v_readfirstlane_b32 s7, v25
	v_readfirstlane_b32 s8, v26
	v_readfirstlane_b32 s9, v27
	s_nop 3
	s_mul_i32 s10, s10, 7
	s_add_i32 s10, s10, s3
	s_add_i32 s10, s10, 1791
	s_lshl_b32 s18, s3, 14
	s_mov_b32 s11, 0x2d00000
	s_cmpk_lt_u32 s10, 0xb00
	s_cbranch_scc1 .Lcv_go_1
	s_cmpk_ge_u32 s10, 0x1400
	s_cbranch_scc1 .Lcv_done_1
	s_add_i32 s10, s10, 0xfffff700
	s_mov_b64 s[4:5], s[6:7]
	s_mov_b32 s11, 0x8900000

; #define LAS __attribute__((address_space(3)))
; __device__ __forceinline__ void conv_plain(const float* W, int K, int N, bf16* WT, int r, LAS unsigned char* scr, int lane, const float* gain_lo = nullptr, const float* gain_hi = nullptr) {
;     const int nrg = N / 64, kb = r / nrg, rg = r % nrg;
;     const float* gain = gain_lo ? (64 * kb < 1024 ? gain_lo : gain_hi - 1024) : nullptr;
;     transpose_item64(W, N, 64 * rg, 32, 64 * rg + 32, 32, K, WT, 64 * rg, 64 * kb, scr, lane, gain);
; __device__ __forceinline__ void convert_item(Frame& F, unsigned char* w, int l, int r, LAS unsigned char* scr) {
;     unsigned char* wl = w + WS_W + (size_t)l * LW_STRIDE;
;     if (r < IT_GU) { conv_gu(inptr(F, 3) + (size_t)l * D * FF, inptr(F, 4) + (size_t)l * D * FF, (bf16*)(wl + LW_GU1), r, scr, F.lane, inptr(F, 2) + (size_t)l * D); return; } r -= IT_GU;
;     if (r < IT_D) { conv_plain(inptr(F, 5) + (size_t)l * FF * D, FF, D, (bf16*)(wl + LW_D1), r, scr, F.lane); return; } r -= IT_D;
;     if (r < IT_IN) { conv_in(inptr(F, 7) + (size_t)l * D * IN_W, (bf16*)(wl + LW_IN), r, scr, F.lane, inptr(F, 6) + (size_t)l * D); return; } r -= IT_IN;
;     if (r < IT_OUT) { conv_plain(inptr(F, 16) + (size_t)l * D * D, D, D, (bf16*)(wl + LW_OUT), r, scr, F.lane, inptr(F, 14) + (size_t)l * 1024, inptr(F, 15) + (size_t)l * 1024); return; } r -= IT_OUT;
;     if (r < IT_GU) { conv_gu(inptr(F, 18) + (size_t)l * D * FF, inptr(F, 19) + (size_t)l * D * FF, (bf16*)(wl + LW_GU2), r, scr, F.lane, inptr(F, 17) + (size_t)l * D); return; } r -= IT_GU;
;     conv_plain(inptr(F, 20) + (size_t)l * FF * D, FF, D, (bf16*)(wl + LW_D2), r, scr, F.lane);
.Lcv_2:
	s_mov_b64 exec, -1
	v_readlane_b32 s2, v255, 2
	s_getreg_b32 s3, hwreg(HW_REG_HW_ID, 0, 6)
	s_nop 3
	s_cmp_ge_u32 s2, 3
	s_cbranch_scc1 .Lcv_done_2
	s_add_i32 s2, s2, 1
	s_lshl_b32 s3, s3, 2
	s_add_i32 s3, s3, 0x20500
	v_mov_b32_e32 v20, s3
	v_mov_b32_e32 v21, 0x20428
	v_mov_b32_e32 v28, 0x204a0
	v_mov_b32_e32 v29, 0x204b0
	ds_read_b32 v20, v20
	ds_read_b64 v[22:23], v21
	ds_read_b64 v[24:25], v28
	ds_read_b64 v[26:27], v29
	v_readlane_b32 s10, v254, 0
	s_waitcnt lgkmcnt(0)
	v_readfirstlane_b32 s3, v20
	v_readfirstlane_b32 s4, v22
	v_readfirstlane_b32 s5, v23
	v_readfirstlane_b32 s6, v24
	v_readfirstlane_b32 s7, v25
	v_readfirstlane_b32 s8, v26
	v_readfirstlane_b32 s9, v27
	s_nop 3
	s_mul_i32 s10, s10, 7
	s_add_i32 s10, s10, s3
	s_add_i32 s10, s10, 3583
	s_lshl_b32 s18, s3, 14
	s_mov_b32 s11, 0x2d00000
	s_cmpk_lt_u32 s10, 0xb00
	s_cbranch_scc1 .Lcv_go_2
	s_cmpk_ge_u32 s10, 0x1400
	s_cbranch_scc1 .Lcv_done_2
	s_add_i32 s10, s10, 0xfffff700
	s_mov_b64 s[4:5], s[6:7]
	s_mov_b32 s11, 0x8900000

; __device__ __forceinline__ void xcd_barrier(const XcdBarrier& b) {
;     ...
;     }
;     __syncthreads();
.Lcv_done_2:
.LBB0_877:
	s_or_b64 exec, exec, s[0:1]
	v_readlane_b32 s4, v254, 0
	v_readlane_b32 s6, v255, 2
	s_waitcnt lgkmcnt(0)
	s_barrier
